# v19 plus nt hint on the sample attention units cached-latent tile loads (read once, cold)
# speedup vs baseline: 1.0024x; 1.0024x over previous
.LBB0_736:
	s_cmp_ge_u32 s90, s91
	s_barrier
	s_waitcnt vmcnt(0)
	ds_write_b128 v184, v[132:135]
	ds_write_b128 v185, v[132:135]
	s_waitcnt vmcnt(4)
	ds_write_b128 v184, v[128:131] offset:10240
	ds_write_b128 v185, v[128:131] offset:4096
	s_waitcnt vmcnt(3)
	ds_write_b128 v184, v[136:139] offset:20480
	ds_write_b128 v185, v[136:139] offset:8192
	s_waitcnt vmcnt(2)
	ds_write_b128 v184, v[140:143] offset:30720
	ds_write_b128 v185, v[140:143] offset:12288
	s_waitcnt vmcnt(1)
	ds_write_b128 v186, v[144:147]
	s_waitcnt vmcnt(0)
	ds_write_b32 v182, v173
	s_waitcnt lgkmcnt(0)
	s_barrier
	s_cbranch_scc1 .LBB0_750
	s_cmp_lg_u32 s24, 0x1e000
	s_cselect_b64 s[28:29], -1, 0
	v_mov_b32_e32 v130, v0
	v_mov_b32_e32 v131, v0
	s_and_b64 s[26:27], s[28:29], exec
	v_mov_b32_e32 v128, v0
	v_mov_b32_e32 v129, v0
	v_mov_b64_e32 v[134:135], v[130:131]
	s_cselect_b32 s27, s97, s23
	s_cselect_b32 s26, s96, s22
	s_or_b64 s[64:65], s[12:13], s[28:29]
	v_mov_b64_e32 v[132:133], v[128:129]
	s_and_saveexec_b64 s[30:31], s[64:65]
	s_cbranch_execz .LBB0_739
	v_lshl_add_u64 v[2:3], s[26:27], 0, v[156:157]
	v_lshlrev_b64 v[2:3], 9, v[2:3]
	v_lshl_add_u64 v[2:3], v[158:159], 0, v[2:3]
	global_load_dwordx4 v[132:135], v[2:3], off nt
.LBB0_739:
	s_or_b64 exec, exec, s[30:31]
	s_or_b64 s[64:65], s[14:15], s[28:29]
	s_and_saveexec_b64 s[30:31], s[64:65]
	s_cbranch_execz .LBB0_741
	v_lshl_add_u64 v[2:3], s[26:27], 0, v[160:161]
	v_lshlrev_b64 v[2:3], 9, v[2:3]
	v_lshl_add_u64 v[2:3], v[158:159], 0, v[2:3]
	global_load_dwordx4 v[128:131], v[2:3], off nt
.LBB0_741:
	s_or_b64 exec, exec, s[30:31]
	v_mov_b32_e32 v2, v0
	v_mov_b32_e32 v3, v0
	v_mov_b32_e32 v1, v0
	v_mov_b64_e32 v[138:139], v[2:3]
	s_or_b64 s[64:65], s[16:17], s[28:29]
	v_mov_b64_e32 v[136:137], v[0:1]
	s_and_saveexec_b64 s[30:31], s[64:65]
	s_cbranch_execz .LBB0_743
	v_lshl_add_u64 v[4:5], s[26:27], 0, v[162:163]
	v_lshlrev_b64 v[4:5], 9, v[4:5]
	v_lshl_add_u64 v[4:5], v[158:159], 0, v[4:5]
	global_load_dwordx4 v[136:139], v[4:5], off nt
.LBB0_743:
	s_or_b64 exec, exec, s[30:31]
	v_mov_b64_e32 v[142:143], v[2:3]
	s_or_b64 s[64:65], s[18:19], s[28:29]
	v_mov_b64_e32 v[140:141], v[0:1]
	s_and_saveexec_b64 s[30:31], s[64:65]
	s_cbranch_execz .LBB0_745
	v_lshl_add_u64 v[2:3], s[26:27], 0, v[164:165]
	v_lshlrev_b64 v[2:3], 9, v[2:3]
	v_lshl_add_u64 v[2:3], v[158:159], 0, v[2:3]
	global_load_dwordx4 v[140:143], v[2:3], off nt
.LBB0_745:
	s_or_b64 exec, exec, s[30:31]
	v_mov_b32_e32 v2, v0
	v_mov_b32_e32 v3, v0
	v_mov_b32_e32 v1, v0
	v_mov_b64_e32 v[146:147], v[2:3]
	s_or_b64 s[30:31], s[10:11], s[28:29]
	v_mov_b64_e32 v[144:145], v[0:1]
	s_and_saveexec_b64 s[64:65], s[30:31]
	s_cbranch_execz .LBB0_747
	s_add_u32 vcc_lo, s94, s24
	s_addc_u32 vcc_hi, s95, s25
	s_and_b64 s[28:29], s[28:29], exec
	s_cselect_b32 s28, vcc_hi, s93
	s_cselect_b32 s29, vcc_lo, s92
	v_mov_b32_e32 v2, s29
	v_mov_b32_e32 v3, s28
	v_lshl_add_u64 v[2:3], v[166:167], 1, v[2:3]
	v_mov_b32_e32 v173, v0
	v_lshl_add_u64 v[2:3], v[2:3], 0, v[172:173]
	global_load_dwordx4 v[144:147], v[2:3], off nt
.LBB0_747:
	s_or_b64 exec, exec, s[64:65]
	v_mov_b32_e32 v173, 0
	s_and_saveexec_b64 s[28:29], s[30:31]
	s_cbranch_execz .LBB0_749
	v_lshl_add_u64 v[2:3], s[26:27], 0, v[154:155]
	v_lshlrev_b64 v[2:3], 5, v[2:3]
	v_lshl_add_u64 v[2:3], v[168:169], 0, v[2:3]
	global_load_dword v173, v[2:3], off nt
